# P1/P6 epilogue loads issued before the ALIGN_EPI barrier (wr=0 waves get their row-scale loads in flight while waiting)
# speedup vs baseline: 1.0234x; 1.0036x over previous
.LBB0_131:
	ds_read_b128 v[146:149], v157
	ds_read_b128 v[150:153], v157 offset:1024
	ds_read_b128 v[160:163], v157 offset:2048
	ds_read_b128 v[164:167], v157 offset:3072
	ds_read_b128 v[168:171], v158
	ds_read_b128 v[172:175], v158 offset:1024
	ds_read_b128 v[176:179], v158 offset:2048
	ds_read_b128 v[180:183], v158 offset:3072
	s_add_u32 s34, s30, 0xfff80080
	s_addc_u32 s35, s31, -1
	s_cmp_eq_u32 s55, 28
	s_cselect_b32 s37, s23, s35
	s_cselect_b32 s36, s51, s34
	s_cselect_b32 s35, s21, s54
	s_cselect_b32 s34, s52, s53
	s_add_u32 s100, s36, 0x80
	s_addc_u32 s101, s37, 0
	s_add_i32 m0, s29, 0xc000
	ds_read_b128 v[184:187], v159
	ds_read_b128 v[188:191], v159 offset:1024
	ds_read_b128 v[192:195], v159 offset:2048
	ds_read_b128 v[196:199], v159 offset:3072
	ds_read_b128 v[200:203], v159 offset:4096
	ds_read_b128 v[204:207], v159 offset:5120
	ds_read_b128 v[208:211], v159 offset:6144
	ds_read_b128 v[212:215], v159 offset:7168
	global_load_lds_dwordx4 v138, s[30:31]
	s_add_i32 m0, s29, 0xe000
	s_nop 0
	global_load_lds_dwordx4 v140, s[30:31]
	s_waitcnt vmcnt(8)
	s_waitcnt lgkmcnt(0)
	s_barrier
	s_waitcnt lgkmcnt(0)
	v_mfma_f32_16x16x32_bf16 v[124:127], v[146:149], v[184:187], v[124:127]
	v_mfma_f32_16x16x32_bf16 v[124:127], v[150:153], v[188:191], v[124:127]
	v_mfma_f32_16x16x32_bf16 v[120:123], v[160:163], v[184:187], v[120:123]
	v_mfma_f32_16x16x32_bf16 v[120:123], v[164:167], v[188:191], v[120:123]
	v_mfma_f32_16x16x32_bf16 v[104:107], v[160:163], v[192:195], v[104:107]
	v_mfma_f32_16x16x32_bf16 v[104:107], v[164:167], v[196:199], v[104:107]
	v_mfma_f32_16x16x32_bf16 v[108:111], v[146:149], v[192:195], v[108:111]
	v_mfma_f32_16x16x32_bf16 v[108:111], v[150:153], v[196:199], v[108:111]
	v_mfma_f32_16x16x32_bf16 v[92:95], v[146:149], v[200:203], v[92:95]
	v_mfma_f32_16x16x32_bf16 v[92:95], v[150:153], v[204:207], v[92:95]
	v_mfma_f32_16x16x32_bf16 v[88:91], v[160:163], v[200:203], v[88:91]
	v_mfma_f32_16x16x32_bf16 v[88:91], v[164:167], v[204:207], v[88:91]
	v_mfma_f32_16x16x32_bf16 v[72:75], v[160:163], v[208:211], v[72:75]
	v_mfma_f32_16x16x32_bf16 v[72:75], v[164:167], v[212:215], v[72:75]
	v_mfma_f32_16x16x32_bf16 v[76:79], v[146:149], v[208:211], v[76:79]
	v_mfma_f32_16x16x32_bf16 v[76:79], v[150:153], v[212:215], v[76:79]
	v_mfma_f32_16x16x32_bf16 v[116:119], v[168:171], v[184:187], v[116:119]
	v_mfma_f32_16x16x32_bf16 v[116:119], v[172:175], v[188:191], v[116:119]
	v_mfma_f32_16x16x32_bf16 v[112:115], v[176:179], v[184:187], v[112:115]
	v_mfma_f32_16x16x32_bf16 v[112:115], v[180:183], v[188:191], v[112:115]
	v_mfma_f32_16x16x32_bf16 v[96:99], v[176:179], v[192:195], v[96:99]
	v_mfma_f32_16x16x32_bf16 v[96:99], v[180:183], v[196:199], v[96:99]
	v_mfma_f32_16x16x32_bf16 v[100:103], v[168:171], v[192:195], v[100:103]
	v_mfma_f32_16x16x32_bf16 v[100:103], v[172:175], v[196:199], v[100:103]
	v_mfma_f32_16x16x32_bf16 v[84:87], v[168:171], v[200:203], v[84:87]
	v_mfma_f32_16x16x32_bf16 v[84:87], v[172:175], v[204:207], v[84:87]
	v_mfma_f32_16x16x32_bf16 v[80:83], v[176:179], v[200:203], v[80:83]
	v_mfma_f32_16x16x32_bf16 v[80:83], v[180:183], v[204:207], v[80:83]
	v_mfma_f32_16x16x32_bf16 v[64:67], v[176:179], v[208:211], v[64:67]
	v_mfma_f32_16x16x32_bf16 v[64:67], v[180:183], v[212:215], v[64:67]
	v_mfma_f32_16x16x32_bf16 v[68:71], v[168:171], v[208:211], v[68:71]
	v_mfma_f32_16x16x32_bf16 v[68:71], v[172:175], v[212:215], v[68:71]
	s_barrier
	s_add_i32 s56, s47, s33
	s_mov_b32 m0, s56
	ds_read_b128 v[184:187], v159 offset:16384
	ds_read_b128 v[188:191], v159 offset:17408
	ds_read_b128 v[192:195], v159 offset:18432
	ds_read_b128 v[196:199], v159 offset:19456
	ds_read_b128 v[200:203], v159 offset:20480
	ds_read_b128 v[204:207], v159 offset:21504
	ds_read_b128 v[208:211], v159 offset:22528
	ds_read_b128 v[212:215], v159 offset:23552
	global_load_lds_dwordx4 v134, s[34:35]
	s_add_i32 m0, s56, 0x2000
	s_add_u32 s56, s34, 0x80000
	s_addc_u32 s57, s35, 0
	s_add_i32 s58, s48, s33
	global_load_lds_dwordx4 v130, s[34:35]
	s_mov_b32 m0, s58
	s_nop 0
	global_load_lds_dwordx4 v134, s[56:57]
	s_add_i32 m0, s58, 0x2000
	s_nop 0
	global_load_lds_dwordx4 v130, s[56:57]
	s_mov_b32 m0, s29
	s_nop 0
	global_load_lds_dwordx4 v136, s[36:37]
	s_mov_b32 m0, s40
	s_nop 0
	global_load_lds_dwordx4 v132, s[36:37]
	s_waitcnt vmcnt(8)
	s_waitcnt lgkmcnt(0)
	s_barrier
	s_waitcnt lgkmcnt(0)
	v_mfma_f32_16x16x32_bf16 v[60:63], v[146:149], v[184:187], v[60:63]
	v_mfma_f32_16x16x32_bf16 v[60:63], v[150:153], v[188:191], v[60:63]
	v_mfma_f32_16x16x32_bf16 v[56:59], v[160:163], v[184:187], v[56:59]
	v_mfma_f32_16x16x32_bf16 v[56:59], v[164:167], v[188:191], v[56:59]
	v_mfma_f32_16x16x32_bf16 v[40:43], v[160:163], v[192:195], v[40:43]
	v_mfma_f32_16x16x32_bf16 v[40:43], v[164:167], v[196:199], v[40:43]
	v_mfma_f32_16x16x32_bf16 v[44:47], v[146:149], v[192:195], v[44:47]
	v_mfma_f32_16x16x32_bf16 v[44:47], v[150:153], v[196:199], v[44:47]
	v_mfma_f32_16x16x32_bf16 v[28:31], v[146:149], v[200:203], v[28:31]
	v_mfma_f32_16x16x32_bf16 v[28:31], v[150:153], v[204:207], v[28:31]
	v_mfma_f32_16x16x32_bf16 v[24:27], v[160:163], v[200:203], v[24:27]
	v_mfma_f32_16x16x32_bf16 v[24:27], v[164:167], v[204:207], v[24:27]
	v_mfma_f32_16x16x32_bf16 v[8:11], v[160:163], v[208:211], v[8:11]
	v_mfma_f32_16x16x32_bf16 v[8:11], v[164:167], v[212:215], v[8:11]
	v_mfma_f32_16x16x32_bf16 v[12:15], v[146:149], v[208:211], v[12:15]
	v_mfma_f32_16x16x32_bf16 v[12:15], v[150:153], v[212:215], v[12:15]
	v_mfma_f32_16x16x32_bf16 v[52:55], v[168:171], v[184:187], v[52:55]
	v_mfma_f32_16x16x32_bf16 v[52:55], v[172:175], v[188:191], v[52:55]
	v_mfma_f32_16x16x32_bf16 v[48:51], v[176:179], v[184:187], v[48:51]
	v_mfma_f32_16x16x32_bf16 v[48:51], v[180:183], v[188:191], v[48:51]
	v_mfma_f32_16x16x32_bf16 v[32:35], v[176:179], v[192:195], v[32:35]
	v_mfma_f32_16x16x32_bf16 v[32:35], v[180:183], v[196:199], v[32:35]
	v_mfma_f32_16x16x32_bf16 v[36:39], v[168:171], v[192:195], v[36:39]
	v_mfma_f32_16x16x32_bf16 v[36:39], v[172:175], v[196:199], v[36:39]
	v_mfma_f32_16x16x32_bf16 v[20:23], v[168:171], v[200:203], v[20:23]
	v_mfma_f32_16x16x32_bf16 v[20:23], v[172:175], v[204:207], v[20:23]
	v_mfma_f32_16x16x32_bf16 v[16:19], v[176:179], v[200:203], v[16:19]
	v_mfma_f32_16x16x32_bf16 v[16:19], v[180:183], v[204:207], v[16:19]
	v_mfma_f32_16x16x32_bf16 v[0:3], v[176:179], v[208:211], v[0:3]
	v_mfma_f32_16x16x32_bf16 v[0:3], v[180:183], v[212:215], v[0:3]
	v_mfma_f32_16x16x32_bf16 v[4:7], v[168:171], v[208:211], v[4:7]
	v_mfma_f32_16x16x32_bf16 v[4:7], v[172:175], v[212:215], v[4:7]
	s_barrier
	s_add_i32 s56, 0, 0x18000
	s_add_i32 s57, 0, 0x1c000
	v_add_u32_e32 v164, s56, v155
	v_add_u32_e32 v180, s57, v155
	ds_read_b128 v[146:149], v164
	ds_read_b128 v[150:153], v164 offset:1024
	ds_read_b128 v[160:163], v164 offset:2048
	ds_read_b128 v[164:167], v164 offset:3072
	ds_read_b128 v[168:171], v180
	ds_read_b128 v[172:175], v180 offset:1024
	ds_read_b128 v[176:179], v180 offset:2048
	ds_read_b128 v[180:183], v180 offset:3072
	s_add_u32 s36, s36, 0x80000
	s_addc_u32 s37, s37, 0
	s_mov_b32 m0, s41
	ds_read_b128 v[184:187], v159 offset:32768
	ds_read_b128 v[188:191], v159 offset:33792
	ds_read_b128 v[192:195], v159 offset:34816
	ds_read_b128 v[196:199], v159 offset:35840
	ds_read_b128 v[200:203], v159 offset:36864
	ds_read_b128 v[204:207], v159 offset:37888
	ds_read_b128 v[208:211], v159 offset:38912
	ds_read_b128 v[212:215], v159 offset:39936
	global_load_lds_dwordx4 v136, s[36:37]
	s_mov_b32 m0, s42
	s_nop 0
	global_load_lds_dwordx4 v132, s[36:37]
	s_waitcnt vmcnt(8)
	s_waitcnt lgkmcnt(0)
	s_barrier
	s_waitcnt lgkmcnt(0)
	v_mfma_f32_16x16x32_bf16 v[124:127], v[146:149], v[184:187], v[124:127]
	v_mfma_f32_16x16x32_bf16 v[124:127], v[150:153], v[188:191], v[124:127]
	v_mfma_f32_16x16x32_bf16 v[120:123], v[160:163], v[184:187], v[120:123]
	v_mfma_f32_16x16x32_bf16 v[120:123], v[164:167], v[188:191], v[120:123]
	v_mfma_f32_16x16x32_bf16 v[104:107], v[160:163], v[192:195], v[104:107]
	v_mfma_f32_16x16x32_bf16 v[104:107], v[164:167], v[196:199], v[104:107]
	v_mfma_f32_16x16x32_bf16 v[108:111], v[146:149], v[192:195], v[108:111]
	v_mfma_f32_16x16x32_bf16 v[108:111], v[150:153], v[196:199], v[108:111]
	v_mfma_f32_16x16x32_bf16 v[92:95], v[146:149], v[200:203], v[92:95]
	v_mfma_f32_16x16x32_bf16 v[92:95], v[150:153], v[204:207], v[92:95]
	v_mfma_f32_16x16x32_bf16 v[88:91], v[160:163], v[200:203], v[88:91]
	v_mfma_f32_16x16x32_bf16 v[88:91], v[164:167], v[204:207], v[88:91]
	v_mfma_f32_16x16x32_bf16 v[72:75], v[160:163], v[208:211], v[72:75]
	v_mfma_f32_16x16x32_bf16 v[72:75], v[164:167], v[212:215], v[72:75]
	v_mfma_f32_16x16x32_bf16 v[76:79], v[146:149], v[208:211], v[76:79]
	v_mfma_f32_16x16x32_bf16 v[76:79], v[150:153], v[212:215], v[76:79]
	v_mfma_f32_16x16x32_bf16 v[116:119], v[168:171], v[184:187], v[116:119]
	v_mfma_f32_16x16x32_bf16 v[116:119], v[172:175], v[188:191], v[116:119]
	v_mfma_f32_16x16x32_bf16 v[112:115], v[176:179], v[184:187], v[112:115]
	v_mfma_f32_16x16x32_bf16 v[112:115], v[180:183], v[188:191], v[112:115]
	v_mfma_f32_16x16x32_bf16 v[96:99], v[176:179], v[192:195], v[96:99]
	v_mfma_f32_16x16x32_bf16 v[96:99], v[180:183], v[196:199], v[96:99]
	v_mfma_f32_16x16x32_bf16 v[100:103], v[168:171], v[192:195], v[100:103]
	v_mfma_f32_16x16x32_bf16 v[100:103], v[172:175], v[196:199], v[100:103]
	v_mfma_f32_16x16x32_bf16 v[84:87], v[168:171], v[200:203], v[84:87]
	v_mfma_f32_16x16x32_bf16 v[84:87], v[172:175], v[204:207], v[84:87]
	v_mfma_f32_16x16x32_bf16 v[80:83], v[176:179], v[200:203], v[80:83]
	v_mfma_f32_16x16x32_bf16 v[80:83], v[180:183], v[204:207], v[80:83]
	v_mfma_f32_16x16x32_bf16 v[64:67], v[176:179], v[208:211], v[64:67]
	v_mfma_f32_16x16x32_bf16 v[64:67], v[180:183], v[212:215], v[64:67]
	v_mfma_f32_16x16x32_bf16 v[68:71], v[168:171], v[208:211], v[68:71]
	v_mfma_f32_16x16x32_bf16 v[68:71], v[172:175], v[212:215], v[68:71]
	s_barrier
	s_add_i32 s36, s56, s33
	s_add_u32 s98, s34, 0x80
	s_addc_u32 s99, s35, 0
	s_mov_b32 m0, s36
	ds_read_b128 v[184:187], v159 offset:49152
	ds_read_b128 v[188:191], v159 offset:50176
	ds_read_b128 v[192:195], v159 offset:51200
	ds_read_b128 v[196:199], v159 offset:52224
	ds_read_b128 v[200:203], v159 offset:53248
	ds_read_b128 v[204:207], v159 offset:54272
	ds_read_b128 v[208:211], v159 offset:55296
	ds_read_b128 v[212:215], v159 offset:56320
	global_load_lds_dwordx4 v134, s[98:99]
	s_add_i32 m0, s36, 0x2000
	s_add_u32 s34, s34, 0x80080
	s_addc_u32 s35, s35, 0
	s_add_i32 s36, s57, s33
	global_load_lds_dwordx4 v130, s[98:99]
	s_mov_b32 m0, s36
	s_nop 0
	global_load_lds_dwordx4 v134, s[34:35]
	s_add_i32 m0, s36, 0x2000
	s_nop 0
	global_load_lds_dwordx4 v130, s[34:35]
	s_mov_b32 m0, s44
	s_nop 0
	global_load_lds_dwordx4 v136, s[100:101]
	s_mov_b32 m0, s45
	s_nop 0
	global_load_lds_dwordx4 v132, s[100:101]
	s_waitcnt vmcnt(8)
	s_waitcnt lgkmcnt(0)
	s_barrier
	s_waitcnt lgkmcnt(0)
	v_mfma_f32_16x16x32_bf16 v[60:63], v[146:149], v[184:187], v[60:63]
	v_mfma_f32_16x16x32_bf16 v[60:63], v[150:153], v[188:191], v[60:63]
	v_mfma_f32_16x16x32_bf16 v[56:59], v[160:163], v[184:187], v[56:59]
	v_mfma_f32_16x16x32_bf16 v[56:59], v[164:167], v[188:191], v[56:59]
	v_mfma_f32_16x16x32_bf16 v[40:43], v[160:163], v[192:195], v[40:43]
	v_mfma_f32_16x16x32_bf16 v[40:43], v[164:167], v[196:199], v[40:43]
	v_mfma_f32_16x16x32_bf16 v[44:47], v[146:149], v[192:195], v[44:47]
	v_mfma_f32_16x16x32_bf16 v[44:47], v[150:153], v[196:199], v[44:47]
	v_mfma_f32_16x16x32_bf16 v[28:31], v[146:149], v[200:203], v[28:31]
	v_mfma_f32_16x16x32_bf16 v[28:31], v[150:153], v[204:207], v[28:31]
	v_mfma_f32_16x16x32_bf16 v[24:27], v[160:163], v[200:203], v[24:27]
	v_mfma_f32_16x16x32_bf16 v[24:27], v[164:167], v[204:207], v[24:27]
	v_mfma_f32_16x16x32_bf16 v[8:11], v[160:163], v[208:211], v[8:11]
	v_mfma_f32_16x16x32_bf16 v[8:11], v[164:167], v[212:215], v[8:11]
	v_mfma_f32_16x16x32_bf16 v[12:15], v[146:149], v[208:211], v[12:15]
	v_mfma_f32_16x16x32_bf16 v[12:15], v[150:153], v[212:215], v[12:15]
	v_mfma_f32_16x16x32_bf16 v[52:55], v[168:171], v[184:187], v[52:55]
	v_mfma_f32_16x16x32_bf16 v[52:55], v[172:175], v[188:191], v[52:55]
	v_mfma_f32_16x16x32_bf16 v[48:51], v[176:179], v[184:187], v[48:51]
	v_mfma_f32_16x16x32_bf16 v[48:51], v[180:183], v[188:191], v[48:51]
	v_mfma_f32_16x16x32_bf16 v[32:35], v[176:179], v[192:195], v[32:35]
	v_mfma_f32_16x16x32_bf16 v[32:35], v[180:183], v[196:199], v[32:35]
	v_mfma_f32_16x16x32_bf16 v[36:39], v[168:171], v[192:195], v[36:39]
	v_mfma_f32_16x16x32_bf16 v[36:39], v[172:175], v[196:199], v[36:39]
	v_mfma_f32_16x16x32_bf16 v[20:23], v[168:171], v[200:203], v[20:23]
	v_mfma_f32_16x16x32_bf16 v[20:23], v[172:175], v[204:207], v[20:23]
	v_mfma_f32_16x16x32_bf16 v[16:19], v[176:179], v[200:203], v[16:19]
	v_mfma_f32_16x16x32_bf16 v[16:19], v[180:183], v[204:207], v[16:19]
	v_mfma_f32_16x16x32_bf16 v[0:3], v[176:179], v[208:211], v[0:3]
	v_mfma_f32_16x16x32_bf16 v[0:3], v[180:183], v[212:215], v[0:3]
	v_mfma_f32_16x16x32_bf16 v[4:7], v[168:171], v[208:211], v[4:7]
	v_mfma_f32_16x16x32_bf16 v[4:7], v[172:175], v[212:215], v[4:7]
	s_barrier
	s_add_i32 s55, s55, 2
	s_add_u32 s30, s30, 0x100
	s_addc_u32 s31, s31, 0
	s_add_u32 s53, s53, 0x100
	s_addc_u32 s54, s54, 0
	s_cmp_gt_u32 s55, 29
	s_cbranch_scc0 .LBB0_131
	v_lshl_add_u32 v146, s28, 8, v154
	v_ashrrev_i32_e32 v147, 31, v146
	v_lshl_add_u64 v[152:153], v[146:147], 2, s[92:93]
	global_load_dword v168, v[152:153], off
	global_load_dword v169, v[152:153], off offset:64
	global_load_dword v170, v[152:153], off offset:128
	global_load_dword v171, v[152:153], off offset:192
	global_load_dword v172, v[152:153], off offset:512
	global_load_dword v173, v[152:153], off offset:576
	global_load_dword v174, v[152:153], off offset:640
	global_load_dword v175, v[152:153], off offset:704
	s_and_b64 vcc, exec, s[18:19]
	s_cbranch_vccz .LBB0_134
	s_barrier
.LBB0_134:
	v_lshl_or_b32 v150, s50, 8, v156
	v_mov_b64_e32 v[148:149], s[8:9]
	v_ashrrev_i32_e32 v151, 31, v150
	v_mad_i64_i32 v[162:163], s[30:31], v146, s49, v[148:149]
	v_lshlrev_b64 v[150:151], 1, v[150:151]
	v_lshl_add_u64 v[162:163], v[162:163], 0, v[150:151]
	s_andn2_b64 vcc, exec, s[0:1]
	s_mov_b64 s[0:1], -1
	s_waitcnt vmcnt(7)
	v_mov_b32_e32 v160, v168
	v_pk_mul_f32 v[126:127], v[126:127], v[160:161] op_sel_hi:[1,0]
	v_pk_mul_f32 v[124:125], v[124:125], v[160:161] op_sel_hi:[1,0]
	v_pk_mul_f32 v[122:123], v[122:123], v[160:161] op_sel_hi:[1,0]
	v_pk_mul_f32 v[120:121], v[120:121], v[160:161] op_sel_hi:[1,0]
	v_pk_mul_f32 v[118:119], v[118:119], v[160:161] op_sel_hi:[1,0]
	v_pk_mul_f32 v[116:117], v[116:117], v[160:161] op_sel_hi:[1,0]
	v_pk_mul_f32 v[164:165], v[114:115], v[160:161] op_sel_hi:[1,0]
	v_pk_mul_f32 v[160:161], v[112:113], v[160:161] op_sel_hi:[1,0]
	v_cvt_pk_bf16_f32 v112, v124, v125
	v_cvt_pk_bf16_f32 v113, v126, v127
	v_cvt_pk_bf16_f32 v114, v120, v121
	v_cvt_pk_bf16_f32 v115, v122, v123
	global_store_dwordx4 v[162:163], v[112:115], off
	s_nop 1
	v_cvt_pk_bf16_f32 v112, v116, v117
	v_cvt_pk_bf16_f32 v113, v118, v119
	v_cvt_pk_bf16_f32 v114, v160, v161
	v_cvt_pk_bf16_f32 v115, v164, v165
	global_store_dwordx4 v[162:163], v[112:115], off offset:256
	s_nop 0
	s_nop 0
	v_or_b32_e32 v113, 16, v146
	v_mad_i64_i32 v[114:115], s[30:31], v113, s49, v[148:149]
	v_lshl_add_u64 v[114:115], v[114:115], 0, v[150:151]
	s_waitcnt vmcnt(8)
	v_mov_b32_e32 v112, v169
	v_pk_mul_f32 v[110:111], v[110:111], v[112:113] op_sel_hi:[1,0]
	v_pk_mul_f32 v[108:109], v[108:109], v[112:113] op_sel_hi:[1,0]
	v_pk_mul_f32 v[106:107], v[106:107], v[112:113] op_sel_hi:[1,0]
	v_pk_mul_f32 v[104:105], v[104:105], v[112:113] op_sel_hi:[1,0]
	v_pk_mul_f32 v[102:103], v[102:103], v[112:113] op_sel_hi:[1,0]
	v_pk_mul_f32 v[100:101], v[100:101], v[112:113] op_sel_hi:[1,0]
	v_pk_mul_f32 v[116:117], v[98:99], v[112:113] op_sel_hi:[1,0]
	v_pk_mul_f32 v[112:113], v[96:97], v[112:113] op_sel_hi:[1,0]
	v_cvt_pk_bf16_f32 v96, v108, v109
	v_cvt_pk_bf16_f32 v97, v110, v111
	v_cvt_pk_bf16_f32 v98, v104, v105
	v_cvt_pk_bf16_f32 v99, v106, v107
	global_store_dwordx4 v[114:115], v[96:99], off
	s_nop 1
	v_cvt_pk_bf16_f32 v96, v100, v101
	v_cvt_pk_bf16_f32 v97, v102, v103
	v_cvt_pk_bf16_f32 v98, v112, v113
	v_cvt_pk_bf16_f32 v99, v116, v117
	global_store_dwordx4 v[114:115], v[96:99], off offset:256
	s_nop 0
	s_nop 0
	v_or_b32_e32 v97, 32, v146
	v_mad_i64_i32 v[98:99], s[30:31], v97, s49, v[148:149]
	v_lshl_add_u64 v[98:99], v[98:99], 0, v[150:151]
	s_waitcnt vmcnt(9)
	v_mov_b32_e32 v96, v170
	v_pk_mul_f32 v[94:95], v[94:95], v[96:97] op_sel_hi:[1,0]
	v_pk_mul_f32 v[92:93], v[92:93], v[96:97] op_sel_hi:[1,0]
	v_pk_mul_f32 v[90:91], v[90:91], v[96:97] op_sel_hi:[1,0]
	v_pk_mul_f32 v[88:89], v[88:89], v[96:97] op_sel_hi:[1,0]
	v_pk_mul_f32 v[86:87], v[86:87], v[96:97] op_sel_hi:[1,0]
	v_pk_mul_f32 v[84:85], v[84:85], v[96:97] op_sel_hi:[1,0]
	v_pk_mul_f32 v[100:101], v[82:83], v[96:97] op_sel_hi:[1,0]
	v_pk_mul_f32 v[96:97], v[80:81], v[96:97] op_sel_hi:[1,0]
	v_cvt_pk_bf16_f32 v80, v92, v93
	v_cvt_pk_bf16_f32 v81, v94, v95
	v_cvt_pk_bf16_f32 v82, v88, v89
	v_cvt_pk_bf16_f32 v83, v90, v91
	global_store_dwordx4 v[98:99], v[80:83], off
	s_nop 1
	v_cvt_pk_bf16_f32 v80, v84, v85
	v_cvt_pk_bf16_f32 v81, v86, v87
	v_cvt_pk_bf16_f32 v82, v96, v97
	v_cvt_pk_bf16_f32 v83, v100, v101
	global_store_dwordx4 v[98:99], v[80:83], off offset:256
	s_nop 0
	s_nop 0
	v_or_b32_e32 v81, 48, v146
	v_mad_i64_i32 v[82:83], s[30:31], v81, s49, v[148:149]
	v_lshl_add_u64 v[82:83], v[82:83], 0, v[150:151]
	s_waitcnt vmcnt(10)
	v_mov_b32_e32 v80, v171
	v_pk_mul_f32 v[78:79], v[78:79], v[80:81] op_sel_hi:[1,0]
	v_pk_mul_f32 v[76:77], v[76:77], v[80:81] op_sel_hi:[1,0]
	v_pk_mul_f32 v[74:75], v[74:75], v[80:81] op_sel_hi:[1,0]
	v_pk_mul_f32 v[72:73], v[72:73], v[80:81] op_sel_hi:[1,0]
	v_pk_mul_f32 v[70:71], v[70:71], v[80:81] op_sel_hi:[1,0]
	v_pk_mul_f32 v[68:69], v[68:69], v[80:81] op_sel_hi:[1,0]
	v_pk_mul_f32 v[84:85], v[66:67], v[80:81] op_sel_hi:[1,0]
	v_pk_mul_f32 v[80:81], v[64:65], v[80:81] op_sel_hi:[1,0]
	v_cvt_pk_bf16_f32 v64, v76, v77
	v_cvt_pk_bf16_f32 v65, v78, v79
	v_cvt_pk_bf16_f32 v66, v72, v73
	v_cvt_pk_bf16_f32 v67, v74, v75
	global_store_dwordx4 v[82:83], v[64:67], off
	s_nop 1
	v_cvt_pk_bf16_f32 v64, v68, v69
	v_cvt_pk_bf16_f32 v65, v70, v71
	v_cvt_pk_bf16_f32 v66, v80, v81
	v_cvt_pk_bf16_f32 v67, v84, v85
	global_store_dwordx4 v[82:83], v[64:67], off offset:256
	s_nop 0
	s_nop 0
	v_add_u32_e32 v65, 0x80, v146
	v_mad_i64_i32 v[66:67], s[30:31], v65, s49, v[148:149]
	v_lshl_add_u64 v[66:67], v[66:67], 0, v[150:151]
	s_waitcnt vmcnt(11)
	v_mov_b32_e32 v64, v172
	v_pk_mul_f32 v[62:63], v[62:63], v[64:65] op_sel_hi:[1,0]
	v_pk_mul_f32 v[60:61], v[60:61], v[64:65] op_sel_hi:[1,0]
	v_pk_mul_f32 v[58:59], v[58:59], v[64:65] op_sel_hi:[1,0]
	v_pk_mul_f32 v[56:57], v[56:57], v[64:65] op_sel_hi:[1,0]
	v_pk_mul_f32 v[54:55], v[54:55], v[64:65] op_sel_hi:[1,0]
	v_pk_mul_f32 v[52:53], v[52:53], v[64:65] op_sel_hi:[1,0]
	v_pk_mul_f32 v[68:69], v[50:51], v[64:65] op_sel_hi:[1,0]
	v_pk_mul_f32 v[64:65], v[48:49], v[64:65] op_sel_hi:[1,0]
	v_cvt_pk_bf16_f32 v48, v60, v61
	v_cvt_pk_bf16_f32 v49, v62, v63
	v_cvt_pk_bf16_f32 v50, v56, v57
	v_cvt_pk_bf16_f32 v51, v58, v59
	global_store_dwordx4 v[66:67], v[48:51], off
	s_nop 1
	v_cvt_pk_bf16_f32 v48, v52, v53
	v_cvt_pk_bf16_f32 v49, v54, v55
	v_cvt_pk_bf16_f32 v50, v64, v65
	v_cvt_pk_bf16_f32 v51, v68, v69
	global_store_dwordx4 v[66:67], v[48:51], off offset:256
	s_nop 0
	s_nop 0
	v_add_u32_e32 v49, 0x90, v146
	v_mad_i64_i32 v[50:51], s[30:31], v49, s49, v[148:149]
	v_lshl_add_u64 v[50:51], v[50:51], 0, v[150:151]
	s_waitcnt vmcnt(12)
	v_mov_b32_e32 v48, v173
	v_pk_mul_f32 v[46:47], v[46:47], v[48:49] op_sel_hi:[1,0]
	v_pk_mul_f32 v[44:45], v[44:45], v[48:49] op_sel_hi:[1,0]
	v_pk_mul_f32 v[42:43], v[42:43], v[48:49] op_sel_hi:[1,0]
	v_pk_mul_f32 v[40:41], v[40:41], v[48:49] op_sel_hi:[1,0]
	v_pk_mul_f32 v[38:39], v[38:39], v[48:49] op_sel_hi:[1,0]
	v_pk_mul_f32 v[36:37], v[36:37], v[48:49] op_sel_hi:[1,0]
	v_pk_mul_f32 v[52:53], v[34:35], v[48:49] op_sel_hi:[1,0]
	v_pk_mul_f32 v[48:49], v[32:33], v[48:49] op_sel_hi:[1,0]
	v_cvt_pk_bf16_f32 v32, v44, v45
	v_cvt_pk_bf16_f32 v33, v46, v47
	v_cvt_pk_bf16_f32 v34, v40, v41
	v_cvt_pk_bf16_f32 v35, v42, v43
	global_store_dwordx4 v[50:51], v[32:35], off
	s_nop 1
	v_cvt_pk_bf16_f32 v32, v36, v37
	v_cvt_pk_bf16_f32 v33, v38, v39
	v_cvt_pk_bf16_f32 v34, v48, v49
	v_cvt_pk_bf16_f32 v35, v52, v53
	global_store_dwordx4 v[50:51], v[32:35], off offset:256
	s_nop 0
	s_nop 0
	v_add_u32_e32 v33, 0xa0, v146
	v_mad_i64_i32 v[34:35], s[30:31], v33, s49, v[148:149]
	v_lshl_add_u64 v[34:35], v[34:35], 0, v[150:151]
	s_waitcnt vmcnt(13)
	v_mov_b32_e32 v32, v174
	v_pk_mul_f32 v[30:31], v[30:31], v[32:33] op_sel_hi:[1,0]
	v_pk_mul_f32 v[28:29], v[28:29], v[32:33] op_sel_hi:[1,0]
	v_pk_mul_f32 v[26:27], v[26:27], v[32:33] op_sel_hi:[1,0]
	v_pk_mul_f32 v[24:25], v[24:25], v[32:33] op_sel_hi:[1,0]
	v_pk_mul_f32 v[22:23], v[22:23], v[32:33] op_sel_hi:[1,0]
	v_pk_mul_f32 v[20:21], v[20:21], v[32:33] op_sel_hi:[1,0]
	v_pk_mul_f32 v[36:37], v[18:19], v[32:33] op_sel_hi:[1,0]
	v_pk_mul_f32 v[32:33], v[16:17], v[32:33] op_sel_hi:[1,0]
	v_cvt_pk_bf16_f32 v16, v28, v29
	v_cvt_pk_bf16_f32 v17, v30, v31
	v_cvt_pk_bf16_f32 v18, v24, v25
	v_cvt_pk_bf16_f32 v19, v26, v27
	global_store_dwordx4 v[34:35], v[16:19], off
	s_nop 1
	v_cvt_pk_bf16_f32 v16, v20, v21
	v_cvt_pk_bf16_f32 v17, v22, v23
	v_cvt_pk_bf16_f32 v18, v32, v33
	v_cvt_pk_bf16_f32 v19, v36, v37
	global_store_dwordx4 v[34:35], v[16:19], off offset:256
	s_nop 0
	s_nop 0
	v_add_u32_e32 v17, 0xb0, v146
	v_mad_i64_i32 v[18:19], s[30:31], v17, s49, v[148:149]
	v_lshl_add_u64 v[18:19], v[18:19], 0, v[150:151]
	s_waitcnt vmcnt(14)
	v_mov_b32_e32 v16, v175
	v_pk_mul_f32 v[14:15], v[14:15], v[16:17] op_sel_hi:[1,0]
	v_pk_mul_f32 v[12:13], v[12:13], v[16:17] op_sel_hi:[1,0]
	v_pk_mul_f32 v[10:11], v[10:11], v[16:17] op_sel_hi:[1,0]
	v_pk_mul_f32 v[8:9], v[8:9], v[16:17] op_sel_hi:[1,0]
	v_pk_mul_f32 v[6:7], v[6:7], v[16:17] op_sel_hi:[1,0]
	v_pk_mul_f32 v[4:5], v[4:5], v[16:17] op_sel_hi:[1,0]
	v_pk_mul_f32 v[20:21], v[2:3], v[16:17] op_sel_hi:[1,0]
	v_pk_mul_f32 v[16:17], v[0:1], v[16:17] op_sel_hi:[1,0]
	v_cvt_pk_bf16_f32 v0, v12, v13
	v_cvt_pk_bf16_f32 v1, v14, v15
	v_cvt_pk_bf16_f32 v2, v8, v9
	v_cvt_pk_bf16_f32 v3, v10, v11
	global_store_dwordx4 v[18:19], v[0:3], off
	s_nop 1
	v_cvt_pk_bf16_f32 v0, v4, v5
	v_cvt_pk_bf16_f32 v1, v6, v7
	v_cvt_pk_bf16_f32 v2, v16, v17
	v_cvt_pk_bf16_f32 v3, v20, v21
	global_store_dwordx4 v[18:19], v[0:3], off offset:256
	s_cbranch_vccnz .LBB0_127
	s_andn2_b64 vcc, exec, s[6:7]
	s_cbranch_vccnz .LBB0_126
	s_barrier
	s_branch .LBB0_126

.LBB0_671:
	ds_read_b128 v[156:159], v151
	ds_read_b128 v[160:163], v151 offset:1024
	ds_read_b128 v[164:167], v151 offset:2048
	ds_read_b128 v[168:171], v151 offset:3072
	ds_read_b128 v[172:175], v152
	ds_read_b128 v[176:179], v152 offset:1024
	ds_read_b128 v[180:183], v152 offset:2048
	ds_read_b128 v[184:187], v152 offset:3072
	s_add_u32 s28, s26, 0xfff80080
	s_addc_u32 s29, s27, -1
	s_cmp_eq_u32 s53, 28
	s_cselect_b32 s31, s19, s29
	s_cselect_b32 s30, s49, s28
	s_cselect_b32 s29, s17, s52
	s_cselect_b32 s28, s50, s51
	s_add_u32 s100, s30, 0x80
	s_addc_u32 s101, s31, 0
	s_add_i32 m0, s25, 0xc000
	ds_read_b128 v[188:191], v153
	ds_read_b128 v[192:195], v153 offset:1024
	ds_read_b128 v[196:199], v153 offset:2048
	ds_read_b128 v[200:203], v153 offset:3072
	ds_read_b128 v[204:207], v153 offset:4096
	ds_read_b128 v[208:211], v153 offset:5120
	ds_read_b128 v[212:215], v153 offset:6144
	ds_read_b128 v[216:219], v153 offset:7168
	global_load_lds_dwordx4 v138, s[26:27]
	s_add_i32 m0, s25, 0xe000
	s_nop 0
	global_load_lds_dwordx4 v140, s[26:27]
	s_waitcnt vmcnt(8)
	s_waitcnt lgkmcnt(0)
	s_barrier
	s_waitcnt lgkmcnt(0)
	v_mfma_f32_16x16x32_bf16 v[116:119], v[156:159], v[188:191], v[116:119]
	v_mfma_f32_16x16x32_bf16 v[116:119], v[160:163], v[192:195], v[116:119]
	v_mfma_f32_16x16x32_bf16 v[112:115], v[164:167], v[188:191], v[112:115]
	v_mfma_f32_16x16x32_bf16 v[112:115], v[168:171], v[192:195], v[112:115]
	v_mfma_f32_16x16x32_bf16 v[96:99], v[164:167], v[196:199], v[96:99]
	v_mfma_f32_16x16x32_bf16 v[96:99], v[168:171], v[200:203], v[96:99]
	v_mfma_f32_16x16x32_bf16 v[100:103], v[156:159], v[196:199], v[100:103]
	v_mfma_f32_16x16x32_bf16 v[100:103], v[160:163], v[200:203], v[100:103]
	v_mfma_f32_16x16x32_bf16 v[84:87], v[156:159], v[204:207], v[84:87]
	v_mfma_f32_16x16x32_bf16 v[84:87], v[160:163], v[208:211], v[84:87]
	v_mfma_f32_16x16x32_bf16 v[80:83], v[164:167], v[204:207], v[80:83]
	v_mfma_f32_16x16x32_bf16 v[80:83], v[168:171], v[208:211], v[80:83]
	v_mfma_f32_16x16x32_bf16 v[64:67], v[164:167], v[212:215], v[64:67]
	v_mfma_f32_16x16x32_bf16 v[64:67], v[168:171], v[216:219], v[64:67]
	v_mfma_f32_16x16x32_bf16 v[68:71], v[156:159], v[212:215], v[68:71]
	v_mfma_f32_16x16x32_bf16 v[68:71], v[160:163], v[216:219], v[68:71]
	v_mfma_f32_16x16x32_bf16 v[124:127], v[172:175], v[188:191], v[124:127]
	v_mfma_f32_16x16x32_bf16 v[124:127], v[176:179], v[192:195], v[124:127]
	v_mfma_f32_16x16x32_bf16 v[120:123], v[180:183], v[188:191], v[120:123]
	v_mfma_f32_16x16x32_bf16 v[120:123], v[184:187], v[192:195], v[120:123]
	v_mfma_f32_16x16x32_bf16 v[104:107], v[180:183], v[196:199], v[104:107]
	v_mfma_f32_16x16x32_bf16 v[104:107], v[184:187], v[200:203], v[104:107]
	v_mfma_f32_16x16x32_bf16 v[108:111], v[172:175], v[196:199], v[108:111]
	v_mfma_f32_16x16x32_bf16 v[108:111], v[176:179], v[200:203], v[108:111]
	v_mfma_f32_16x16x32_bf16 v[92:95], v[172:175], v[204:207], v[92:95]
	v_mfma_f32_16x16x32_bf16 v[92:95], v[176:179], v[208:211], v[92:95]
	v_mfma_f32_16x16x32_bf16 v[88:91], v[180:183], v[204:207], v[88:91]
	v_mfma_f32_16x16x32_bf16 v[88:91], v[184:187], v[208:211], v[88:91]
	v_mfma_f32_16x16x32_bf16 v[72:75], v[180:183], v[212:215], v[72:75]
	v_mfma_f32_16x16x32_bf16 v[72:75], v[184:187], v[216:219], v[72:75]
	v_mfma_f32_16x16x32_bf16 v[76:79], v[172:175], v[212:215], v[76:79]
	v_mfma_f32_16x16x32_bf16 v[76:79], v[176:179], v[216:219], v[76:79]
	s_barrier
	s_add_i32 s54, s46, s36
	s_mov_b32 m0, s54
	ds_read_b128 v[188:191], v153 offset:16384
	ds_read_b128 v[192:195], v153 offset:17408
	ds_read_b128 v[196:199], v153 offset:18432
	ds_read_b128 v[200:203], v153 offset:19456
	ds_read_b128 v[204:207], v153 offset:20480
	ds_read_b128 v[208:211], v153 offset:21504
	ds_read_b128 v[212:215], v153 offset:22528
	ds_read_b128 v[216:219], v153 offset:23552
	global_load_lds_dwordx4 v134, s[28:29]
	s_add_i32 m0, s54, 0x2000
	s_add_u32 s54, s28, 0x80000
	s_addc_u32 s55, s29, 0
	s_add_i32 s56, s47, s36
	global_load_lds_dwordx4 v130, s[28:29]
	s_mov_b32 m0, s56
	s_nop 0
	global_load_lds_dwordx4 v134, s[54:55]
	s_add_i32 m0, s56, 0x2000
	s_nop 0
	global_load_lds_dwordx4 v130, s[54:55]
	s_mov_b32 m0, s25
	s_nop 0
	global_load_lds_dwordx4 v136, s[30:31]
	s_mov_b32 m0, s39
	s_nop 0
	global_load_lds_dwordx4 v132, s[30:31]
	s_waitcnt vmcnt(8)
	s_waitcnt lgkmcnt(0)
	s_barrier
	s_waitcnt lgkmcnt(0)
	v_mfma_f32_16x16x32_bf16 v[52:55], v[156:159], v[188:191], v[52:55]
	v_mfma_f32_16x16x32_bf16 v[52:55], v[160:163], v[192:195], v[52:55]
	v_mfma_f32_16x16x32_bf16 v[48:51], v[164:167], v[188:191], v[48:51]
	v_mfma_f32_16x16x32_bf16 v[48:51], v[168:171], v[192:195], v[48:51]
	v_mfma_f32_16x16x32_bf16 v[32:35], v[164:167], v[196:199], v[32:35]
	v_mfma_f32_16x16x32_bf16 v[32:35], v[168:171], v[200:203], v[32:35]
	v_mfma_f32_16x16x32_bf16 v[36:39], v[156:159], v[196:199], v[36:39]
	v_mfma_f32_16x16x32_bf16 v[36:39], v[160:163], v[200:203], v[36:39]
	v_mfma_f32_16x16x32_bf16 v[20:23], v[156:159], v[204:207], v[20:23]
	v_mfma_f32_16x16x32_bf16 v[20:23], v[160:163], v[208:211], v[20:23]
	v_mfma_f32_16x16x32_bf16 v[16:19], v[164:167], v[204:207], v[16:19]
	v_mfma_f32_16x16x32_bf16 v[16:19], v[168:171], v[208:211], v[16:19]
	v_mfma_f32_16x16x32_bf16 v[0:3], v[164:167], v[212:215], v[0:3]
	v_mfma_f32_16x16x32_bf16 v[0:3], v[168:171], v[216:219], v[0:3]
	v_mfma_f32_16x16x32_bf16 v[8:11], v[156:159], v[212:215], v[8:11]
	v_mfma_f32_16x16x32_bf16 v[8:11], v[160:163], v[216:219], v[8:11]
	v_mfma_f32_16x16x32_bf16 v[60:63], v[172:175], v[188:191], v[60:63]
	v_mfma_f32_16x16x32_bf16 v[60:63], v[176:179], v[192:195], v[60:63]
	v_mfma_f32_16x16x32_bf16 v[56:59], v[180:183], v[188:191], v[56:59]
	v_mfma_f32_16x16x32_bf16 v[56:59], v[184:187], v[192:195], v[56:59]
	v_mfma_f32_16x16x32_bf16 v[40:43], v[180:183], v[196:199], v[40:43]
	v_mfma_f32_16x16x32_bf16 v[40:43], v[184:187], v[200:203], v[40:43]
	v_mfma_f32_16x16x32_bf16 v[44:47], v[172:175], v[196:199], v[44:47]
	v_mfma_f32_16x16x32_bf16 v[44:47], v[176:179], v[200:203], v[44:47]
	v_mfma_f32_16x16x32_bf16 v[28:31], v[172:175], v[204:207], v[28:31]
	v_mfma_f32_16x16x32_bf16 v[28:31], v[176:179], v[208:211], v[28:31]
	v_mfma_f32_16x16x32_bf16 v[24:27], v[180:183], v[204:207], v[24:27]
	v_mfma_f32_16x16x32_bf16 v[24:27], v[184:187], v[208:211], v[24:27]
	v_mfma_f32_16x16x32_bf16 v[4:7], v[180:183], v[212:215], v[4:7]
	v_mfma_f32_16x16x32_bf16 v[4:7], v[184:187], v[216:219], v[4:7]
	v_mfma_f32_16x16x32_bf16 v[12:15], v[172:175], v[212:215], v[12:15]
	v_mfma_f32_16x16x32_bf16 v[12:15], v[176:179], v[216:219], v[12:15]
	s_barrier
	s_add_i32 s54, 0, 0x18000
	v_add_u32_e32 v155, s54, v149
	s_add_i32 s55, 0, 0x1c000
	ds_read_b128 v[156:159], v155
	ds_read_b128 v[160:163], v155 offset:1024
	ds_read_b128 v[164:167], v155 offset:2048
	ds_read_b128 v[168:171], v155 offset:3072
	v_add_u32_e32 v155, s55, v149
	ds_read_b128 v[172:175], v155
	ds_read_b128 v[176:179], v155 offset:1024
	ds_read_b128 v[180:183], v155 offset:2048
	ds_read_b128 v[184:187], v155 offset:3072
	s_add_u32 s30, s30, 0x80000
	s_addc_u32 s31, s31, 0
	s_mov_b32 m0, s40
	ds_read_b128 v[188:191], v153 offset:32768
	ds_read_b128 v[192:195], v153 offset:33792
	ds_read_b128 v[196:199], v153 offset:34816
	ds_read_b128 v[200:203], v153 offset:35840
	ds_read_b128 v[204:207], v153 offset:36864
	ds_read_b128 v[208:211], v153 offset:37888
	ds_read_b128 v[212:215], v153 offset:38912
	ds_read_b128 v[216:219], v153 offset:39936
	global_load_lds_dwordx4 v136, s[30:31]
	s_mov_b32 m0, s41
	s_nop 0
	global_load_lds_dwordx4 v132, s[30:31]
	s_waitcnt vmcnt(8)
	s_waitcnt lgkmcnt(0)
	s_barrier
	s_waitcnt lgkmcnt(0)
	v_mfma_f32_16x16x32_bf16 v[116:119], v[156:159], v[188:191], v[116:119]
	v_mfma_f32_16x16x32_bf16 v[116:119], v[160:163], v[192:195], v[116:119]
	v_mfma_f32_16x16x32_bf16 v[112:115], v[164:167], v[188:191], v[112:115]
	v_mfma_f32_16x16x32_bf16 v[112:115], v[168:171], v[192:195], v[112:115]
	v_mfma_f32_16x16x32_bf16 v[96:99], v[164:167], v[196:199], v[96:99]
	v_mfma_f32_16x16x32_bf16 v[96:99], v[168:171], v[200:203], v[96:99]
	v_mfma_f32_16x16x32_bf16 v[100:103], v[156:159], v[196:199], v[100:103]
	v_mfma_f32_16x16x32_bf16 v[100:103], v[160:163], v[200:203], v[100:103]
	v_mfma_f32_16x16x32_bf16 v[84:87], v[156:159], v[204:207], v[84:87]
	v_mfma_f32_16x16x32_bf16 v[84:87], v[160:163], v[208:211], v[84:87]
	v_mfma_f32_16x16x32_bf16 v[80:83], v[164:167], v[204:207], v[80:83]
	v_mfma_f32_16x16x32_bf16 v[80:83], v[168:171], v[208:211], v[80:83]
	v_mfma_f32_16x16x32_bf16 v[64:67], v[164:167], v[212:215], v[64:67]
	v_mfma_f32_16x16x32_bf16 v[64:67], v[168:171], v[216:219], v[64:67]
	v_mfma_f32_16x16x32_bf16 v[68:71], v[156:159], v[212:215], v[68:71]
	v_mfma_f32_16x16x32_bf16 v[68:71], v[160:163], v[216:219], v[68:71]
	v_mfma_f32_16x16x32_bf16 v[124:127], v[172:175], v[188:191], v[124:127]
	v_mfma_f32_16x16x32_bf16 v[124:127], v[176:179], v[192:195], v[124:127]
	v_mfma_f32_16x16x32_bf16 v[120:123], v[180:183], v[188:191], v[120:123]
	v_mfma_f32_16x16x32_bf16 v[120:123], v[184:187], v[192:195], v[120:123]
	v_mfma_f32_16x16x32_bf16 v[104:107], v[180:183], v[196:199], v[104:107]
	v_mfma_f32_16x16x32_bf16 v[104:107], v[184:187], v[200:203], v[104:107]
	v_mfma_f32_16x16x32_bf16 v[108:111], v[172:175], v[196:199], v[108:111]
	v_mfma_f32_16x16x32_bf16 v[108:111], v[176:179], v[200:203], v[108:111]
	v_mfma_f32_16x16x32_bf16 v[92:95], v[172:175], v[204:207], v[92:95]
	v_mfma_f32_16x16x32_bf16 v[92:95], v[176:179], v[208:211], v[92:95]
	v_mfma_f32_16x16x32_bf16 v[88:91], v[180:183], v[204:207], v[88:91]
	v_mfma_f32_16x16x32_bf16 v[88:91], v[184:187], v[208:211], v[88:91]
	v_mfma_f32_16x16x32_bf16 v[72:75], v[180:183], v[212:215], v[72:75]
	v_mfma_f32_16x16x32_bf16 v[72:75], v[184:187], v[216:219], v[72:75]
	v_mfma_f32_16x16x32_bf16 v[76:79], v[172:175], v[212:215], v[76:79]
	v_mfma_f32_16x16x32_bf16 v[76:79], v[176:179], v[216:219], v[76:79]
	s_barrier
	s_add_i32 s30, s54, s36
	s_add_u32 s98, s28, 0x80
	s_addc_u32 s99, s29, 0
	s_mov_b32 m0, s30
	ds_read_b128 v[188:191], v153 offset:49152
	ds_read_b128 v[192:195], v153 offset:50176
	ds_read_b128 v[196:199], v153 offset:51200
	ds_read_b128 v[200:203], v153 offset:52224
	ds_read_b128 v[204:207], v153 offset:53248
	ds_read_b128 v[208:211], v153 offset:54272
	ds_read_b128 v[212:215], v153 offset:55296
	ds_read_b128 v[216:219], v153 offset:56320
	global_load_lds_dwordx4 v134, s[98:99]
	s_add_i32 m0, s30, 0x2000
	s_add_u32 s28, s28, 0x80080
	s_addc_u32 s29, s29, 0
	s_add_i32 s30, s55, s36
	global_load_lds_dwordx4 v130, s[98:99]
	s_mov_b32 m0, s30
	s_nop 0
	global_load_lds_dwordx4 v134, s[28:29]
	s_add_i32 m0, s30, 0x2000
	s_nop 0
	global_load_lds_dwordx4 v130, s[28:29]
	s_mov_b32 m0, s43
	s_nop 0
	global_load_lds_dwordx4 v136, s[100:101]
	s_mov_b32 m0, s44
	s_nop 0
	global_load_lds_dwordx4 v132, s[100:101]
	s_waitcnt vmcnt(8)
	s_waitcnt lgkmcnt(0)
	s_barrier
	s_waitcnt lgkmcnt(0)
	v_mfma_f32_16x16x32_bf16 v[52:55], v[156:159], v[188:191], v[52:55]
	v_mfma_f32_16x16x32_bf16 v[52:55], v[160:163], v[192:195], v[52:55]
	v_mfma_f32_16x16x32_bf16 v[48:51], v[164:167], v[188:191], v[48:51]
	v_mfma_f32_16x16x32_bf16 v[48:51], v[168:171], v[192:195], v[48:51]
	v_mfma_f32_16x16x32_bf16 v[32:35], v[164:167], v[196:199], v[32:35]
	v_mfma_f32_16x16x32_bf16 v[32:35], v[168:171], v[200:203], v[32:35]
	v_mfma_f32_16x16x32_bf16 v[36:39], v[156:159], v[196:199], v[36:39]
	v_mfma_f32_16x16x32_bf16 v[36:39], v[160:163], v[200:203], v[36:39]
	v_mfma_f32_16x16x32_bf16 v[20:23], v[156:159], v[204:207], v[20:23]
	v_mfma_f32_16x16x32_bf16 v[20:23], v[160:163], v[208:211], v[20:23]
	v_mfma_f32_16x16x32_bf16 v[16:19], v[164:167], v[204:207], v[16:19]
	v_mfma_f32_16x16x32_bf16 v[16:19], v[168:171], v[208:211], v[16:19]
	v_mfma_f32_16x16x32_bf16 v[0:3], v[164:167], v[212:215], v[0:3]
	v_mfma_f32_16x16x32_bf16 v[0:3], v[168:171], v[216:219], v[0:3]
	v_mfma_f32_16x16x32_bf16 v[8:11], v[156:159], v[212:215], v[8:11]
	v_mfma_f32_16x16x32_bf16 v[8:11], v[160:163], v[216:219], v[8:11]
	v_mfma_f32_16x16x32_bf16 v[60:63], v[172:175], v[188:191], v[60:63]
	v_mfma_f32_16x16x32_bf16 v[60:63], v[176:179], v[192:195], v[60:63]
	v_mfma_f32_16x16x32_bf16 v[56:59], v[180:183], v[188:191], v[56:59]
	v_mfma_f32_16x16x32_bf16 v[56:59], v[184:187], v[192:195], v[56:59]
	v_mfma_f32_16x16x32_bf16 v[40:43], v[180:183], v[196:199], v[40:43]
	v_mfma_f32_16x16x32_bf16 v[40:43], v[184:187], v[200:203], v[40:43]
	v_mfma_f32_16x16x32_bf16 v[44:47], v[172:175], v[196:199], v[44:47]
	v_mfma_f32_16x16x32_bf16 v[44:47], v[176:179], v[200:203], v[44:47]
	v_mfma_f32_16x16x32_bf16 v[28:31], v[172:175], v[204:207], v[28:31]
	v_mfma_f32_16x16x32_bf16 v[28:31], v[176:179], v[208:211], v[28:31]
	v_mfma_f32_16x16x32_bf16 v[24:27], v[180:183], v[204:207], v[24:27]
	v_mfma_f32_16x16x32_bf16 v[24:27], v[184:187], v[208:211], v[24:27]
	v_mfma_f32_16x16x32_bf16 v[4:7], v[180:183], v[212:215], v[4:7]
	v_mfma_f32_16x16x32_bf16 v[4:7], v[184:187], v[216:219], v[4:7]
	v_mfma_f32_16x16x32_bf16 v[12:15], v[172:175], v[212:215], v[12:15]
	v_mfma_f32_16x16x32_bf16 v[12:15], v[176:179], v[216:219], v[12:15]
	s_barrier
	s_add_i32 s53, s53, 2
	s_add_u32 s26, s26, 0x100
	s_addc_u32 s27, s27, 0
	s_add_u32 s51, s51, 0x100
	s_addc_u32 s52, s52, 0
	s_cmp_gt_u32 s53, 29
	s_cbranch_scc0 .LBB0_671
	v_lshl_add_u32 v146, s24, 8, v148
	v_lshlrev_b32_e32 v147, 5, v146
	v_add_u32_e32 v254, 0x1000, v147
	global_load_dwordx4 v[156:159], v147, s[10:11]
	global_load_dwordx4 v[160:163], v147, s[10:11] offset:16
	global_load_dwordx4 v[164:167], v147, s[10:11] offset:512
	global_load_dwordx4 v[168:171], v147, s[10:11] offset:528
	global_load_dwordx4 v[172:175], v147, s[10:11] offset:1024
	global_load_dwordx4 v[176:179], v147, s[10:11] offset:1040
	global_load_dwordx4 v[180:183], v147, s[10:11] offset:1536
	global_load_dwordx4 v[184:187], v147, s[10:11] offset:1552
	global_load_dwordx4 v[188:191], v254, s[10:11]
	global_load_dwordx4 v[192:195], v254, s[10:11] offset:16
	global_load_dwordx4 v[196:199], v254, s[10:11] offset:512
	global_load_dwordx4 v[200:203], v254, s[10:11] offset:528
	global_load_dwordx4 v[204:207], v254, s[10:11] offset:1024
	global_load_dwordx4 v[208:211], v254, s[10:11] offset:1040
	global_load_dwordx4 v[212:215], v254, s[10:11] offset:1536
	global_load_dwordx4 v[216:219], v254, s[10:11] offset:1552
	v_mul_u32_u24_e32 v155, 0x2c00, v146
	v_lshl_or_b32 v255, s2, 7, v150
	v_mov_b32_e32 v252, 0xbfb8aa3b
	v_mov_b32_e32 v253, 1.0
	v_lshl_add_u32 v155, v255, 1, v155
	s_and_b64 vcc, exec, s[14:15]
	s_cbranch_vccz .LBB0_674
	s_barrier
.LBB0_674:
	s_andn2_b64 vcc, exec, s[0:1]
	s_mov_b64 s[0:1], -1
	s_waitcnt vmcnt(14)
	v_add_f32_e32 v156, v156, v157
	v_add_f32_e32 v158, v158, v159
	v_add_f32_e32 v160, v160, v161
	v_add_f32_e32 v162, v162, v163
	v_add_f32_e32 v156, v156, v158
	v_add_f32_e32 v160, v160, v162
	v_add_f32_e32 v156, v156, v160
	v_fmamk_f32 v156, v156, 0x3a000000, v154
	v_rsq_f32_e32 v146, v156
	v_mov_b32_e32 v147, v155
	v_pk_mul_f32 v[116:117], v[116:117], v[146:147] op_sel_hi:[1,0]
	v_pk_mul_f32 v[118:119], v[118:119], v[146:147] op_sel_hi:[1,0]
	v_pk_mul_f32 v[112:113], v[112:113], v[146:147] op_sel_hi:[1,0]
	v_pk_mul_f32 v[114:115], v[114:115], v[146:147] op_sel_hi:[1,0]
	v_pk_mul_f32 v[124:125], v[124:125], v[146:147] op_sel_hi:[1,0]
	v_pk_mul_f32 v[126:127], v[126:127], v[146:147] op_sel_hi:[1,0]
	v_pk_mul_f32 v[120:121], v[120:121], v[146:147] op_sel_hi:[1,0]
	v_pk_mul_f32 v[122:123], v[122:123], v[146:147] op_sel_hi:[1,0]
	v_pk_mul_f32 v[156:157], v[116:117], v[252:253] op_sel_hi:[1,0]
	v_pk_mul_f32 v[158:159], v[118:119], v[252:253] op_sel_hi:[1,0]
	v_pk_mul_f32 v[160:161], v[112:113], v[252:253] op_sel_hi:[1,0]
	v_pk_mul_f32 v[162:163], v[114:115], v[252:253] op_sel_hi:[1,0]
	v_exp_f32_e32 v156, v156
	v_exp_f32_e32 v157, v157
	v_exp_f32_e32 v158, v158
	v_exp_f32_e32 v159, v159
	v_exp_f32_e32 v160, v160
	v_exp_f32_e32 v161, v161
	v_exp_f32_e32 v162, v162
	v_exp_f32_e32 v163, v163
	v_pk_add_f32 v[156:157], v[156:157], v[252:253] op_sel:[0,1]
	v_pk_add_f32 v[158:159], v[158:159], v[252:253] op_sel:[0,1]
	v_pk_add_f32 v[160:161], v[160:161], v[252:253] op_sel:[0,1]
	v_pk_add_f32 v[162:163], v[162:163], v[252:253] op_sel:[0,1]
	v_rcp_f32_e32 v156, v156
	v_rcp_f32_e32 v157, v157
	v_rcp_f32_e32 v158, v158
	v_rcp_f32_e32 v159, v159
	v_rcp_f32_e32 v160, v160
	v_rcp_f32_e32 v161, v161
	v_rcp_f32_e32 v162, v162
	v_rcp_f32_e32 v163, v163
	v_pk_mul_f32 v[116:117], v[116:117], v[156:157]
	v_pk_mul_f32 v[118:119], v[118:119], v[158:159]
	v_pk_mul_f32 v[112:113], v[112:113], v[160:161]
	v_pk_mul_f32 v[114:115], v[114:115], v[162:163]
	v_pk_mul_f32 v[116:117], v[124:125], v[116:117]
	v_pk_mul_f32 v[118:119], v[126:127], v[118:119]
	v_pk_mul_f32 v[112:113], v[120:121], v[112:113]
	v_pk_mul_f32 v[114:115], v[122:123], v[114:115]
	v_cvt_pk_bf16_f32 v120, v116, v117
	v_cvt_pk_bf16_f32 v121, v118, v119
	v_cvt_pk_bf16_f32 v122, v112, v113
	v_cvt_pk_bf16_f32 v123, v114, v115
	global_store_dwordx4 v147, v[120:123], s[8:9]
	s_waitcnt vmcnt(13)
	v_add_f32_e32 v164, v164, v165
	v_add_f32_e32 v166, v166, v167
	v_add_f32_e32 v168, v168, v169
	v_add_f32_e32 v170, v170, v171
	v_add_f32_e32 v164, v164, v166
	v_add_f32_e32 v168, v168, v170
	v_add_f32_e32 v164, v164, v168
	v_fmamk_f32 v164, v164, 0x3a000000, v154
	v_rsq_f32_e32 v146, v164
	v_add_u32_e32 v147, 0x2c000, v155
	v_pk_mul_f32 v[100:101], v[100:101], v[146:147] op_sel_hi:[1,0]
	v_pk_mul_f32 v[102:103], v[102:103], v[146:147] op_sel_hi:[1,0]
	v_pk_mul_f32 v[96:97], v[96:97], v[146:147] op_sel_hi:[1,0]
	v_pk_mul_f32 v[98:99], v[98:99], v[146:147] op_sel_hi:[1,0]
	v_pk_mul_f32 v[108:109], v[108:109], v[146:147] op_sel_hi:[1,0]
	v_pk_mul_f32 v[110:111], v[110:111], v[146:147] op_sel_hi:[1,0]
	v_pk_mul_f32 v[104:105], v[104:105], v[146:147] op_sel_hi:[1,0]
	v_pk_mul_f32 v[106:107], v[106:107], v[146:147] op_sel_hi:[1,0]
	v_pk_mul_f32 v[164:165], v[100:101], v[252:253] op_sel_hi:[1,0]
	v_pk_mul_f32 v[166:167], v[102:103], v[252:253] op_sel_hi:[1,0]
	v_pk_mul_f32 v[168:169], v[96:97], v[252:253] op_sel_hi:[1,0]
	v_pk_mul_f32 v[170:171], v[98:99], v[252:253] op_sel_hi:[1,0]
	v_exp_f32_e32 v164, v164
	v_exp_f32_e32 v165, v165
	v_exp_f32_e32 v166, v166
	v_exp_f32_e32 v167, v167
	v_exp_f32_e32 v168, v168
	v_exp_f32_e32 v169, v169
	v_exp_f32_e32 v170, v170
	v_exp_f32_e32 v171, v171
	v_pk_add_f32 v[164:165], v[164:165], v[252:253] op_sel:[0,1]
	v_pk_add_f32 v[166:167], v[166:167], v[252:253] op_sel:[0,1]
	v_pk_add_f32 v[168:169], v[168:169], v[252:253] op_sel:[0,1]
	v_pk_add_f32 v[170:171], v[170:171], v[252:253] op_sel:[0,1]
	v_rcp_f32_e32 v164, v164
	v_rcp_f32_e32 v165, v165
	v_rcp_f32_e32 v166, v166
	v_rcp_f32_e32 v167, v167
	v_rcp_f32_e32 v168, v168
	v_rcp_f32_e32 v169, v169
	v_rcp_f32_e32 v170, v170
	v_rcp_f32_e32 v171, v171
	v_pk_mul_f32 v[100:101], v[100:101], v[164:165]
	v_pk_mul_f32 v[102:103], v[102:103], v[166:167]
	v_pk_mul_f32 v[96:97], v[96:97], v[168:169]
	v_pk_mul_f32 v[98:99], v[98:99], v[170:171]
	v_pk_mul_f32 v[100:101], v[108:109], v[100:101]
	v_pk_mul_f32 v[102:103], v[110:111], v[102:103]
	v_pk_mul_f32 v[96:97], v[104:105], v[96:97]
	v_pk_mul_f32 v[98:99], v[106:107], v[98:99]
	v_cvt_pk_bf16_f32 v104, v100, v101
	v_cvt_pk_bf16_f32 v105, v102, v103
	v_cvt_pk_bf16_f32 v106, v96, v97
	v_cvt_pk_bf16_f32 v107, v98, v99
	global_store_dwordx4 v147, v[104:107], s[8:9]
	s_waitcnt vmcnt(12)
	v_add_f32_e32 v172, v172, v173
	v_add_f32_e32 v174, v174, v175
	v_add_f32_e32 v176, v176, v177
	v_add_f32_e32 v178, v178, v179
	v_add_f32_e32 v172, v172, v174
	v_add_f32_e32 v176, v176, v178
	v_add_f32_e32 v172, v172, v176
	v_fmamk_f32 v172, v172, 0x3a000000, v154
	v_rsq_f32_e32 v146, v172
	v_add_u32_e32 v147, 0x58000, v155
	v_pk_mul_f32 v[84:85], v[84:85], v[146:147] op_sel_hi:[1,0]
	v_pk_mul_f32 v[86:87], v[86:87], v[146:147] op_sel_hi:[1,0]
	v_pk_mul_f32 v[80:81], v[80:81], v[146:147] op_sel_hi:[1,0]
	v_pk_mul_f32 v[82:83], v[82:83], v[146:147] op_sel_hi:[1,0]
	v_pk_mul_f32 v[92:93], v[92:93], v[146:147] op_sel_hi:[1,0]
	v_pk_mul_f32 v[94:95], v[94:95], v[146:147] op_sel_hi:[1,0]
	v_pk_mul_f32 v[88:89], v[88:89], v[146:147] op_sel_hi:[1,0]
	v_pk_mul_f32 v[90:91], v[90:91], v[146:147] op_sel_hi:[1,0]
	v_pk_mul_f32 v[172:173], v[84:85], v[252:253] op_sel_hi:[1,0]
	v_pk_mul_f32 v[174:175], v[86:87], v[252:253] op_sel_hi:[1,0]
	v_pk_mul_f32 v[176:177], v[80:81], v[252:253] op_sel_hi:[1,0]
	v_pk_mul_f32 v[178:179], v[82:83], v[252:253] op_sel_hi:[1,0]
	v_exp_f32_e32 v172, v172
	v_exp_f32_e32 v173, v173
	v_exp_f32_e32 v174, v174
	v_exp_f32_e32 v175, v175
	v_exp_f32_e32 v176, v176
	v_exp_f32_e32 v177, v177
	v_exp_f32_e32 v178, v178
	v_exp_f32_e32 v179, v179
	v_pk_add_f32 v[172:173], v[172:173], v[252:253] op_sel:[0,1]
	v_pk_add_f32 v[174:175], v[174:175], v[252:253] op_sel:[0,1]
	v_pk_add_f32 v[176:177], v[176:177], v[252:253] op_sel:[0,1]
	v_pk_add_f32 v[178:179], v[178:179], v[252:253] op_sel:[0,1]
	v_rcp_f32_e32 v172, v172
	v_rcp_f32_e32 v173, v173
	v_rcp_f32_e32 v174, v174
	v_rcp_f32_e32 v175, v175
	v_rcp_f32_e32 v176, v176
	v_rcp_f32_e32 v177, v177
	v_rcp_f32_e32 v178, v178
	v_rcp_f32_e32 v179, v179
	v_pk_mul_f32 v[84:85], v[84:85], v[172:173]
	v_pk_mul_f32 v[86:87], v[86:87], v[174:175]
	v_pk_mul_f32 v[80:81], v[80:81], v[176:177]
	v_pk_mul_f32 v[82:83], v[82:83], v[178:179]
	v_pk_mul_f32 v[84:85], v[92:93], v[84:85]
	v_pk_mul_f32 v[86:87], v[94:95], v[86:87]
	v_pk_mul_f32 v[80:81], v[88:89], v[80:81]
	v_pk_mul_f32 v[82:83], v[90:91], v[82:83]
	v_cvt_pk_bf16_f32 v88, v84, v85
	v_cvt_pk_bf16_f32 v89, v86, v87
	v_cvt_pk_bf16_f32 v90, v80, v81
	v_cvt_pk_bf16_f32 v91, v82, v83
	global_store_dwordx4 v147, v[88:91], s[8:9]
	s_waitcnt vmcnt(11)
	v_add_f32_e32 v180, v180, v181
	v_add_f32_e32 v182, v182, v183
	v_add_f32_e32 v184, v184, v185
	v_add_f32_e32 v186, v186, v187
	v_add_f32_e32 v180, v180, v182
	v_add_f32_e32 v184, v184, v186
	v_add_f32_e32 v180, v180, v184
	v_fmamk_f32 v180, v180, 0x3a000000, v154
	v_rsq_f32_e32 v146, v180
	v_add_u32_e32 v147, 0x84000, v155
	v_pk_mul_f32 v[68:69], v[68:69], v[146:147] op_sel_hi:[1,0]
	v_pk_mul_f32 v[70:71], v[70:71], v[146:147] op_sel_hi:[1,0]
	v_pk_mul_f32 v[64:65], v[64:65], v[146:147] op_sel_hi:[1,0]
	v_pk_mul_f32 v[66:67], v[66:67], v[146:147] op_sel_hi:[1,0]
	v_pk_mul_f32 v[76:77], v[76:77], v[146:147] op_sel_hi:[1,0]
	v_pk_mul_f32 v[78:79], v[78:79], v[146:147] op_sel_hi:[1,0]
	v_pk_mul_f32 v[72:73], v[72:73], v[146:147] op_sel_hi:[1,0]
	v_pk_mul_f32 v[74:75], v[74:75], v[146:147] op_sel_hi:[1,0]
	v_pk_mul_f32 v[180:181], v[68:69], v[252:253] op_sel_hi:[1,0]
	v_pk_mul_f32 v[182:183], v[70:71], v[252:253] op_sel_hi:[1,0]
	v_pk_mul_f32 v[184:185], v[64:65], v[252:253] op_sel_hi:[1,0]
	v_pk_mul_f32 v[186:187], v[66:67], v[252:253] op_sel_hi:[1,0]
	v_exp_f32_e32 v180, v180
	v_exp_f32_e32 v181, v181
	v_exp_f32_e32 v182, v182
	v_exp_f32_e32 v183, v183
	v_exp_f32_e32 v184, v184
	v_exp_f32_e32 v185, v185
	v_exp_f32_e32 v186, v186
	v_exp_f32_e32 v187, v187
	v_pk_add_f32 v[180:181], v[180:181], v[252:253] op_sel:[0,1]
	v_pk_add_f32 v[182:183], v[182:183], v[252:253] op_sel:[0,1]
	v_pk_add_f32 v[184:185], v[184:185], v[252:253] op_sel:[0,1]
	v_pk_add_f32 v[186:187], v[186:187], v[252:253] op_sel:[0,1]
	v_rcp_f32_e32 v180, v180
	v_rcp_f32_e32 v181, v181
	v_rcp_f32_e32 v182, v182
	v_rcp_f32_e32 v183, v183
	v_rcp_f32_e32 v184, v184
	v_rcp_f32_e32 v185, v185
	v_rcp_f32_e32 v186, v186
	v_rcp_f32_e32 v187, v187
	v_pk_mul_f32 v[68:69], v[68:69], v[180:181]
	v_pk_mul_f32 v[70:71], v[70:71], v[182:183]
	v_pk_mul_f32 v[64:65], v[64:65], v[184:185]
	v_pk_mul_f32 v[66:67], v[66:67], v[186:187]
	v_pk_mul_f32 v[68:69], v[76:77], v[68:69]
	v_pk_mul_f32 v[70:71], v[78:79], v[70:71]
	v_pk_mul_f32 v[64:65], v[72:73], v[64:65]
	v_pk_mul_f32 v[66:67], v[74:75], v[66:67]
	v_cvt_pk_bf16_f32 v72, v68, v69
	v_cvt_pk_bf16_f32 v73, v70, v71
	v_cvt_pk_bf16_f32 v74, v64, v65
	v_cvt_pk_bf16_f32 v75, v66, v67
	global_store_dwordx4 v147, v[72:75], s[8:9]
	s_waitcnt vmcnt(10)
	v_add_f32_e32 v188, v188, v189
	v_add_f32_e32 v190, v190, v191
	v_add_f32_e32 v192, v192, v193
	v_add_f32_e32 v194, v194, v195
	v_add_f32_e32 v188, v188, v190
	v_add_f32_e32 v192, v192, v194
	v_add_f32_e32 v188, v188, v192
	v_fmamk_f32 v188, v188, 0x3a000000, v154
	v_rsq_f32_e32 v146, v188
	v_add_u32_e32 v147, 0x160000, v155
	v_pk_mul_f32 v[52:53], v[52:53], v[146:147] op_sel_hi:[1,0]
	v_pk_mul_f32 v[54:55], v[54:55], v[146:147] op_sel_hi:[1,0]
	v_pk_mul_f32 v[48:49], v[48:49], v[146:147] op_sel_hi:[1,0]
	v_pk_mul_f32 v[50:51], v[50:51], v[146:147] op_sel_hi:[1,0]
	v_pk_mul_f32 v[60:61], v[60:61], v[146:147] op_sel_hi:[1,0]
	v_pk_mul_f32 v[62:63], v[62:63], v[146:147] op_sel_hi:[1,0]
	v_pk_mul_f32 v[56:57], v[56:57], v[146:147] op_sel_hi:[1,0]
	v_pk_mul_f32 v[58:59], v[58:59], v[146:147] op_sel_hi:[1,0]
	v_pk_mul_f32 v[188:189], v[52:53], v[252:253] op_sel_hi:[1,0]
	v_pk_mul_f32 v[190:191], v[54:55], v[252:253] op_sel_hi:[1,0]
	v_pk_mul_f32 v[192:193], v[48:49], v[252:253] op_sel_hi:[1,0]
	v_pk_mul_f32 v[194:195], v[50:51], v[252:253] op_sel_hi:[1,0]
	v_exp_f32_e32 v188, v188
	v_exp_f32_e32 v189, v189
	v_exp_f32_e32 v190, v190
	v_exp_f32_e32 v191, v191
	v_exp_f32_e32 v192, v192
	v_exp_f32_e32 v193, v193
	v_exp_f32_e32 v194, v194
	v_exp_f32_e32 v195, v195
	v_pk_add_f32 v[188:189], v[188:189], v[252:253] op_sel:[0,1]
	v_pk_add_f32 v[190:191], v[190:191], v[252:253] op_sel:[0,1]
	v_pk_add_f32 v[192:193], v[192:193], v[252:253] op_sel:[0,1]
	v_pk_add_f32 v[194:195], v[194:195], v[252:253] op_sel:[0,1]
	v_rcp_f32_e32 v188, v188
	v_rcp_f32_e32 v189, v189
	v_rcp_f32_e32 v190, v190
	v_rcp_f32_e32 v191, v191
	v_rcp_f32_e32 v192, v192
	v_rcp_f32_e32 v193, v193
	v_rcp_f32_e32 v194, v194
	v_rcp_f32_e32 v195, v195
	v_pk_mul_f32 v[52:53], v[52:53], v[188:189]
	v_pk_mul_f32 v[54:55], v[54:55], v[190:191]
	v_pk_mul_f32 v[48:49], v[48:49], v[192:193]
	v_pk_mul_f32 v[50:51], v[50:51], v[194:195]
	v_pk_mul_f32 v[52:53], v[60:61], v[52:53]
	v_pk_mul_f32 v[54:55], v[62:63], v[54:55]
	v_pk_mul_f32 v[48:49], v[56:57], v[48:49]
	v_pk_mul_f32 v[50:51], v[58:59], v[50:51]
	v_cvt_pk_bf16_f32 v56, v52, v53
	v_cvt_pk_bf16_f32 v57, v54, v55
	v_cvt_pk_bf16_f32 v58, v48, v49
	v_cvt_pk_bf16_f32 v59, v50, v51
	global_store_dwordx4 v147, v[56:59], s[8:9]
	s_waitcnt vmcnt(9)
	v_add_f32_e32 v196, v196, v197
	v_add_f32_e32 v198, v198, v199
	v_add_f32_e32 v200, v200, v201
	v_add_f32_e32 v202, v202, v203
	v_add_f32_e32 v196, v196, v198
	v_add_f32_e32 v200, v200, v202
	v_add_f32_e32 v196, v196, v200
	v_fmamk_f32 v196, v196, 0x3a000000, v154
	v_rsq_f32_e32 v146, v196
	v_add_u32_e32 v147, 0x18c000, v155
	v_pk_mul_f32 v[36:37], v[36:37], v[146:147] op_sel_hi:[1,0]
	v_pk_mul_f32 v[38:39], v[38:39], v[146:147] op_sel_hi:[1,0]
	v_pk_mul_f32 v[32:33], v[32:33], v[146:147] op_sel_hi:[1,0]
	v_pk_mul_f32 v[34:35], v[34:35], v[146:147] op_sel_hi:[1,0]
	v_pk_mul_f32 v[44:45], v[44:45], v[146:147] op_sel_hi:[1,0]
	v_pk_mul_f32 v[46:47], v[46:47], v[146:147] op_sel_hi:[1,0]
	v_pk_mul_f32 v[40:41], v[40:41], v[146:147] op_sel_hi:[1,0]
	v_pk_mul_f32 v[42:43], v[42:43], v[146:147] op_sel_hi:[1,0]
	v_pk_mul_f32 v[196:197], v[36:37], v[252:253] op_sel_hi:[1,0]
	v_pk_mul_f32 v[198:199], v[38:39], v[252:253] op_sel_hi:[1,0]
	v_pk_mul_f32 v[200:201], v[32:33], v[252:253] op_sel_hi:[1,0]
	v_pk_mul_f32 v[202:203], v[34:35], v[252:253] op_sel_hi:[1,0]
	v_exp_f32_e32 v196, v196
	v_exp_f32_e32 v197, v197
	v_exp_f32_e32 v198, v198
	v_exp_f32_e32 v199, v199
	v_exp_f32_e32 v200, v200
	v_exp_f32_e32 v201, v201
	v_exp_f32_e32 v202, v202
	v_exp_f32_e32 v203, v203
	v_pk_add_f32 v[196:197], v[196:197], v[252:253] op_sel:[0,1]
	v_pk_add_f32 v[198:199], v[198:199], v[252:253] op_sel:[0,1]
	v_pk_add_f32 v[200:201], v[200:201], v[252:253] op_sel:[0,1]
	v_pk_add_f32 v[202:203], v[202:203], v[252:253] op_sel:[0,1]
	v_rcp_f32_e32 v196, v196
	v_rcp_f32_e32 v197, v197
	v_rcp_f32_e32 v198, v198
	v_rcp_f32_e32 v199, v199
	v_rcp_f32_e32 v200, v200
	v_rcp_f32_e32 v201, v201
	v_rcp_f32_e32 v202, v202
	v_rcp_f32_e32 v203, v203
	v_pk_mul_f32 v[36:37], v[36:37], v[196:197]
	v_pk_mul_f32 v[38:39], v[38:39], v[198:199]
	v_pk_mul_f32 v[32:33], v[32:33], v[200:201]
	v_pk_mul_f32 v[34:35], v[34:35], v[202:203]
	v_pk_mul_f32 v[36:37], v[44:45], v[36:37]
	v_pk_mul_f32 v[38:39], v[46:47], v[38:39]
	v_pk_mul_f32 v[32:33], v[40:41], v[32:33]
	v_pk_mul_f32 v[34:35], v[42:43], v[34:35]
	v_cvt_pk_bf16_f32 v40, v36, v37
	v_cvt_pk_bf16_f32 v41, v38, v39
	v_cvt_pk_bf16_f32 v42, v32, v33
	v_cvt_pk_bf16_f32 v43, v34, v35
	global_store_dwordx4 v147, v[40:43], s[8:9]
	s_waitcnt vmcnt(8)
	v_add_f32_e32 v204, v204, v205
	v_add_f32_e32 v206, v206, v207
	v_add_f32_e32 v208, v208, v209
	v_add_f32_e32 v210, v210, v211
	v_add_f32_e32 v204, v204, v206
	v_add_f32_e32 v208, v208, v210
	v_add_f32_e32 v204, v204, v208
	v_fmamk_f32 v204, v204, 0x3a000000, v154
	v_rsq_f32_e32 v146, v204
	v_add_u32_e32 v147, 0x1b8000, v155
	v_pk_mul_f32 v[20:21], v[20:21], v[146:147] op_sel_hi:[1,0]
	v_pk_mul_f32 v[22:23], v[22:23], v[146:147] op_sel_hi:[1,0]
	v_pk_mul_f32 v[16:17], v[16:17], v[146:147] op_sel_hi:[1,0]
	v_pk_mul_f32 v[18:19], v[18:19], v[146:147] op_sel_hi:[1,0]
	v_pk_mul_f32 v[28:29], v[28:29], v[146:147] op_sel_hi:[1,0]
	v_pk_mul_f32 v[30:31], v[30:31], v[146:147] op_sel_hi:[1,0]
	v_pk_mul_f32 v[24:25], v[24:25], v[146:147] op_sel_hi:[1,0]
	v_pk_mul_f32 v[26:27], v[26:27], v[146:147] op_sel_hi:[1,0]
	v_pk_mul_f32 v[204:205], v[20:21], v[252:253] op_sel_hi:[1,0]
	v_pk_mul_f32 v[206:207], v[22:23], v[252:253] op_sel_hi:[1,0]
	v_pk_mul_f32 v[208:209], v[16:17], v[252:253] op_sel_hi:[1,0]
	v_pk_mul_f32 v[210:211], v[18:19], v[252:253] op_sel_hi:[1,0]
	v_exp_f32_e32 v204, v204
	v_exp_f32_e32 v205, v205
	v_exp_f32_e32 v206, v206
	v_exp_f32_e32 v207, v207
	v_exp_f32_e32 v208, v208
	v_exp_f32_e32 v209, v209
	v_exp_f32_e32 v210, v210
	v_exp_f32_e32 v211, v211
	v_pk_add_f32 v[204:205], v[204:205], v[252:253] op_sel:[0,1]
	v_pk_add_f32 v[206:207], v[206:207], v[252:253] op_sel:[0,1]
	v_pk_add_f32 v[208:209], v[208:209], v[252:253] op_sel:[0,1]
	v_pk_add_f32 v[210:211], v[210:211], v[252:253] op_sel:[0,1]
	v_rcp_f32_e32 v204, v204
	v_rcp_f32_e32 v205, v205
	v_rcp_f32_e32 v206, v206
	v_rcp_f32_e32 v207, v207
	v_rcp_f32_e32 v208, v208
	v_rcp_f32_e32 v209, v209
	v_rcp_f32_e32 v210, v210
	v_rcp_f32_e32 v211, v211
	v_pk_mul_f32 v[20:21], v[20:21], v[204:205]
	v_pk_mul_f32 v[22:23], v[22:23], v[206:207]
	v_pk_mul_f32 v[16:17], v[16:17], v[208:209]
	v_pk_mul_f32 v[18:19], v[18:19], v[210:211]
	v_pk_mul_f32 v[20:21], v[28:29], v[20:21]
	v_pk_mul_f32 v[22:23], v[30:31], v[22:23]
	v_pk_mul_f32 v[16:17], v[24:25], v[16:17]
	v_pk_mul_f32 v[18:19], v[26:27], v[18:19]
	v_cvt_pk_bf16_f32 v24, v20, v21
	v_cvt_pk_bf16_f32 v25, v22, v23
	v_cvt_pk_bf16_f32 v26, v16, v17
	v_cvt_pk_bf16_f32 v27, v18, v19
	global_store_dwordx4 v147, v[24:27], s[8:9]
	s_waitcnt vmcnt(7)
	v_add_f32_e32 v212, v212, v213
	v_add_f32_e32 v214, v214, v215
	v_add_f32_e32 v216, v216, v217
	v_add_f32_e32 v218, v218, v219
	v_add_f32_e32 v212, v212, v214
	v_add_f32_e32 v216, v216, v218
	v_add_f32_e32 v212, v212, v216
	v_fmamk_f32 v212, v212, 0x3a000000, v154
	v_rsq_f32_e32 v146, v212
	v_add_u32_e32 v147, 0x1e4000, v155
	v_pk_mul_f32 v[8:9], v[8:9], v[146:147] op_sel_hi:[1,0]
	v_pk_mul_f32 v[10:11], v[10:11], v[146:147] op_sel_hi:[1,0]
	v_pk_mul_f32 v[0:1], v[0:1], v[146:147] op_sel_hi:[1,0]
	v_pk_mul_f32 v[2:3], v[2:3], v[146:147] op_sel_hi:[1,0]
	v_pk_mul_f32 v[12:13], v[12:13], v[146:147] op_sel_hi:[1,0]
	v_pk_mul_f32 v[14:15], v[14:15], v[146:147] op_sel_hi:[1,0]
	v_pk_mul_f32 v[4:5], v[4:5], v[146:147] op_sel_hi:[1,0]
	v_pk_mul_f32 v[6:7], v[6:7], v[146:147] op_sel_hi:[1,0]
	v_pk_mul_f32 v[212:213], v[8:9], v[252:253] op_sel_hi:[1,0]
	v_pk_mul_f32 v[214:215], v[10:11], v[252:253] op_sel_hi:[1,0]
	v_pk_mul_f32 v[216:217], v[0:1], v[252:253] op_sel_hi:[1,0]
	v_pk_mul_f32 v[218:219], v[2:3], v[252:253] op_sel_hi:[1,0]
	v_exp_f32_e32 v212, v212
	v_exp_f32_e32 v213, v213
	v_exp_f32_e32 v214, v214
	v_exp_f32_e32 v215, v215
	v_exp_f32_e32 v216, v216
	v_exp_f32_e32 v217, v217
	v_exp_f32_e32 v218, v218
	v_exp_f32_e32 v219, v219
	v_pk_add_f32 v[212:213], v[212:213], v[252:253] op_sel:[0,1]
	v_pk_add_f32 v[214:215], v[214:215], v[252:253] op_sel:[0,1]
	v_pk_add_f32 v[216:217], v[216:217], v[252:253] op_sel:[0,1]
	v_pk_add_f32 v[218:219], v[218:219], v[252:253] op_sel:[0,1]
	v_rcp_f32_e32 v212, v212
	v_rcp_f32_e32 v213, v213
	v_rcp_f32_e32 v214, v214
	v_rcp_f32_e32 v215, v215
	v_rcp_f32_e32 v216, v216
	v_rcp_f32_e32 v217, v217
	v_rcp_f32_e32 v218, v218
	v_rcp_f32_e32 v219, v219
	v_pk_mul_f32 v[8:9], v[8:9], v[212:213]
	v_pk_mul_f32 v[10:11], v[10:11], v[214:215]
	v_pk_mul_f32 v[0:1], v[0:1], v[216:217]
	v_pk_mul_f32 v[2:3], v[2:3], v[218:219]
	v_pk_mul_f32 v[8:9], v[12:13], v[8:9]
	v_pk_mul_f32 v[10:11], v[14:15], v[10:11]
	v_pk_mul_f32 v[0:1], v[4:5], v[0:1]
	v_pk_mul_f32 v[2:3], v[6:7], v[2:3]
	v_cvt_pk_bf16_f32 v4, v8, v9
	v_cvt_pk_bf16_f32 v5, v10, v11
	v_cvt_pk_bf16_f32 v6, v0, v1
	v_cvt_pk_bf16_f32 v7, v2, v3
	global_store_dwordx4 v147, v[4:7], s[8:9]
	s_cbranch_vccnz .LBB0_667
	s_andn2_b64 vcc, exec, s[6:7]
	s_cbranch_vccnz .LBB0_666
	s_barrier
	s_branch .LBB0_666
